# speedup vs baseline: 1.0054x; 1.0054x over previous
; __device__ __forceinline__ u16 f2bf(float a) { return (u16)(pack2(a, 0.f) & 0xffffu); }
;     ...
;   {
;     int k = t >> 3, n0 = (t & 7) * 8;
;     const float4* s = (const float4*)(src + (size_t)(kt * 64 + k) * N + ntile * 64 + n0);
;     float4 a = s[0], b = s[1];
;     tl[(n0 + 0) * 66 + k] = f2bf(a.x); tl[(n0 + 1) * 66 + k] = f2bf(a.y);
;     tl[(n0 + 2) * 66 + k] = f2bf(a.z); tl[(n0 + 3) * 66 + k] = f2bf(a.w);
;     tl[(n0 + 4) * 66 + k] = f2bf(b.x); tl[(n0 + 5) * 66 + k] = f2bf(b.y);
;     tl[(n0 + 6) * 66 + k] = f2bf(b.z); tl[(n0 + 7) * 66 + k] = f2bf(b.w);
;   }
;   __syncthreads();
;   {
;     int n = t >> 3, kk0 = (t & 7) * 8;
;     int ng = ntile * 64 + n, np = ng;
;     if (mode == 1) {
;       if (ng >= 1792) { int j = ng - 1792; int hb = 0; if (j >= 1024) { j -= 1024; hb = 32; } np = 1792 + (j >> 5) * 64 + hb + (j & 31); }
;     } else if (mode == 2) {
;       int j = ng, hb = 0; if (j >= DFF) { j -= DFF; hb = 32; } np = (j >> 5) * 64 + hb + (j & 31);
;     }
;     const uint32_t* r = (const uint32_t*)(tl + n * 66 + kk0);
;     uint4 v = make_uint4(r[0], r[1], r[2], r[3]);
;     *(uint4*)(dst + (size_t)np * dld + kt * 64 + kk0) = v;
; __global__ void __launch_bounds__(NTHREADS, 2) fwd_megakernel(Params p_arg) {
;     ...
;     for (int t = blockIdx.x; t < NLAYER * 3584; t += gridDim.x) {
;       int l = t / 3584, r = t - l * 3584;
;       u16* wl = WB + (size_t)l * WLAYER_E;
;       if (r < 960) { transpose_tile(pk->w_in + (size_t)l * 1024 * INW, wl + WOFF_IN, 1024, INW, r / 60, r % 60, 1, shm, tid); }
;       else if (r < 1088) { r -= 960; transpose_tile(pk->w_a + (size_t)l * 512 * 1024, wl + WOFF_A, 512, 1024, r / 16, r % 16, 0, shm, tid, 1024); }
;       else if (r < 1216) { r -= 1088; transpose_tile(pk->w_b + (size_t)l * 512 * 1024, wl + WOFF_A + 512, 512, 1024, r / 16, r % 16, 0, shm, tid, 1024); }
;       else if (r < 1472) { r -= 1216; transpose_tile(pk->w_o + (size_t)l * 1024 * 1024, wl + WOFF_O, 1024, 1024, r / 16, r % 16, 0, shm, tid); }
;       else if (r < 2880) { r -= 1472; transpose_tile(pk->w_ffn_in + (size_t)l * 1024 * 2 * DFF, wl + WOFF_FI, 1024, 2 * DFF, r / 88, r % 88, 2, shm, tid); }
;       else { r -= 2880; transpose_tile(pk->w_ffn_out + (size_t)l * DFF * 1024, wl + WOFF_FO, DFF, 1024, r / 16, r % 16, 0, shm, tid); }
.LBB0_34:
	s_or_b64 exec, exec, s[34:35]
	v_mov_b32_e32 v3, 0
	s_waitcnt lgkmcnt(0)
	s_barrier
	ds_read_b128 v[4:7], v3
	s_and_b32 s6, s2, 7
	s_waitcnt lgkmcnt(0)
	s_barrier
	v_readfirstlane_b32 s4, v5
	v_readfirstlane_b32 s7, v4
	v_readfirstlane_b32 s16, v7
	v_writelane_b32 v255, s4, 1
	v_readfirstlane_b32 s4, v6
	s_lshr_b32 s10, s16, 16
	s_and_b32 s5, s16, 0xffff
	v_writelane_b32 v255, s4, 2
	v_writelane_b32 v255, s0, 3
	s_mov_b64 s[8:9], s[0:1]
	s_sub_i32 s4, s7, s6
	v_writelane_b32 v255, s1, 4
	v_mbcnt_lo_u32_b32 v0, -1, 0
	v_mbcnt_hi_u32_b32 v0, -1, v0
	s_mul_i32 s4, s10, s4
	v_readlane_b32 s0, v255, 0
	s_add_i32 s6, s4, s6
	s_lshr_b32 s4, s2, 3
	v_add_u32_e32 v0, s0, v0
	s_load_dwordx2 s[0:1], s[8:9], 0x98
	s_load_dwordx2 s[42:43], s[8:9], 0x88
	s_load_dwordx2 s[44:45], s[8:9], 0x80
	s_load_dwordx2 s[46:47], s[8:9], 0x70
	s_load_dwordx2 s[48:49], s[8:9], 0x68
	s_load_dwordx2 s[50:51], s[8:9], 0x60
	s_load_dwordx2 s[52:53], s[8:9], 0x28
	s_sub_i32 s5, s5, s4
	s_mul_i32 s40, s5, s10
	s_add_i32 s40, s40, s4
	v_writelane_b32 v255, s10, 5
	s_cmpk_lt_i32 s2, 0x3800
	v_readfirstlane_b32 s17, v0
	s_cbranch_scc0 .LBB0_59
	v_ashrrev_i32_e32 v1, 3, v0
	v_lshlrev_b32_e32 v2, 3, v0
	v_and_b32_e32 v4, 56, v2
	v_lshlrev_b32_e32 v2, 1, v1
	s_movk_i32 s4, 0x84
	v_mad_u32_u24 v8, v4, s4, v2
	v_mul_lo_u32 v2, v1, s4
	v_lshl_add_u32 v9, v4, 1, v2
	v_and_b32_e32 v10, 31, v1
	s_lshl_b32 s18, s2, 3
	s_lshl_b32 s19, s3, 3
	s_lshl_b32 s20, s2, 7
	s_lshl_b32 s21, s3, 7
	s_mov_b32 s5, 0
	s_movk_i32 s26, 0x1600
	s_movk_i32 s27, 0x5800
	s_movk_i32 s28, 0xaff
	s_movk_i32 s29, 0x3c00
	s_movk_i32 s30, 0x6ff
	v_lshlrev_b32_e32 v2, 2, v4
	v_lshlrev_b32_e32 v4, 1, v4
	v_mov_b32_e32 v11, 0xfffff900
	v_mov_b32_e32 v12, 0xfffff500
	s_lshl_b32 s31, s2, 1
	s_branch .LBB0_38
.LBB0_36:
	s_or_b64 exec, exec, s[14:15]
	v_ashrrev_i32_e32 v7, 31, v6
	ds_read2_b32 v[14:15], v9 offset1:1
	ds_read2_b32 v[16:17], v9 offset0:2 offset1:3
	v_lshlrev_b64 v[6:7], 11, v[6:7]
	v_lshl_add_u64 v[6:7], s[10:11], 0, v[6:7]
	s_ashr_i32 s13, s12, 31
	v_lshl_add_u64 v[6:7], s[12:13], 1, v[6:7]
	v_mov_b32_e32 v5, v3
	v_lshl_add_u64 v[6:7], v[6:7], 0, v[4:5]
	s_waitcnt lgkmcnt(0)
	global_store_dwordx4 v[6:7], v[14:17], off
	v_xor_b32_e32 v8, 0x4000, v8
	v_xor_b32_e32 v9, 0x4000, v9
	s_cmp_lg_u32 s57, 0
	s_cbranch_scc1 .LBB0_37
	s_mov_b32 s57, 1
	s_add_i32 s33, s33, 1
	s_mov_b32 s12, s56
	s_branch .Lwin_again
.LBB0_37:
	v_xor_b32_e32 v8, 0x8000, v8
	v_xor_b32_e32 v9, 0x8000, v9
	s_add_i32 s31, s31, s3
	s_add_i32 s31, s31, s3
	s_add_i32 s18, s18, s19
	s_add_i32 s20, s20, s21
	s_cmpk_gt_i32 s31, 0x37ff
	s_cbranch_scc1 .LBB0_59
.LBB0_38:
	s_mul_hi_i32 s4, s31, 0x92492493
	s_add_i32 s4, s4, s31
	s_lshr_b32 s10, s4, 31
	s_ashr_i32 s4, s4, 11
	s_add_i32 s12, s4, s10
	s_mul_i32 s4, s12, 0xfffff200
	s_add_i32 s33, s31, s4
	s_ashr_i32 s13, s12, 31
	s_mul_i32 s10, s12, 0x1c40000
	s_mul_hi_i32 s4, s12, 0x1c40000
	s_waitcnt lgkmcnt(0)
	s_add_u32 s10, s0, s10
	s_addc_u32 s11, s1, s4
	s_cmpk_gt_i32 s33, 0x3bf
	s_mov_b64 s[14:15], -1
	s_cbranch_scc0 .LBB0_56
	s_cmpk_gt_u32 s33, 0x43f
	s_cbranch_scc0 .LBB0_53
	s_cmpk_gt_u32 s33, 0x4bf
	s_cbranch_scc0 .LBB0_50
	s_cmpk_gt_u32 s33, 0x5bf
	s_cbranch_scc0 .LBB0_47
	s_cmpk_gt_u32 s33, 0xb3f
	s_cbranch_scc0 .LBB0_44
	s_mov_b64 s[14:15], s[42:43]
	s_mul_i32 s34, s12, 0xb00000
	s_mul_hi_i32 s4, s12, 0xb00000
	s_mul_i32 s35, s12, 0xffffc800
	v_mov_b32_e32 v5, v3
	s_waitcnt lgkmcnt(0)
	s_add_u32 s14, s14, s34
	s_addc_u32 s15, s15, s4
	s_add_i32 s4, s18, s35
	s_andn2_b32 s4, s4, 63
	s_add_i32 s34, s4, 0xffffd300
	v_add_u32_e32 v6, s34, v1
	v_ashrrev_i32_e32 v7, 31, v6
	v_lshlrev_b64 v[6:7], 12, v[6:7]
	v_lshl_add_u64 v[6:7], s[14:15], 0, v[6:7]
	s_and_b32 s14, s20, 0x3c0
	s_lshl_b32 s4, s14, 2
	v_lshl_add_u64 v[6:7], v[6:7], 0, s[4:5]
	v_lshl_add_u64 v[6:7], v[6:7], 0, v[2:3]
	global_load_dwordx4 v[14:17], v[6:7], off
	global_load_dwordx4 v[18:21], v[6:7], off offset:16
	global_load_dwordx4 v[44:47], v[6:7], off offset:256
	global_load_dwordx4 v[48:51], v[6:7], off offset:272
	v_mov_b64_e32 v[6:7], s[10:11]
	v_add_u32_e32 v13, s14, v1
	s_mov_b32 s35, s5
	v_mad_i64_i32 v[6:7], s[14:15], v13, s26, v[6:7]
	v_lshl_add_u64 v[6:7], s[34:35], 1, v[6:7]
	v_lshl_add_u64 v[6:7], v[6:7], 0, v[4:5]
	v_add_co_u32_e32 v6, vcc, 0x1680000, v6
	s_mov_b64 s[14:15], 0
	s_nop 0
	v_addc_co_u32_e32 v7, vcc, 0, v7, vcc
	s_waitcnt vmcnt(3)
	v_cvt_pk_bf16_f32 v5, v14, s0
	v_cvt_pk_bf16_f32 v13, v15, s0
	v_cvt_pk_bf16_f32 v14, v16, s0
	v_cvt_pk_bf16_f32 v15, v17, s0
	s_waitcnt vmcnt(2)
	v_cvt_pk_bf16_f32 v16, v18, s0
	v_cvt_pk_bf16_f32 v17, v19, s0
	v_cvt_pk_bf16_f32 v18, v20, s0
	v_cvt_pk_bf16_f32 v19, v21, s0
	ds_write_b16 v8, v5
	ds_write_b16 v8, v13 offset:132
	ds_write_b16 v8, v14 offset:264
	ds_write_b16 v8, v15 offset:396
	ds_write_b16 v8, v16 offset:528
	ds_write_b16 v8, v17 offset:660
	ds_write_b16 v8, v18 offset:792
	ds_write_b16 v8, v19 offset:924
	s_waitcnt vmcnt(1)
	v_cvt_pk_bf16_f32 v52, v44, s0
	v_cvt_pk_bf16_f32 v53, v45, s0
	v_cvt_pk_bf16_f32 v54, v46, s0
	v_cvt_pk_bf16_f32 v55, v47, s0
	s_waitcnt vmcnt(0)
	v_cvt_pk_bf16_f32 v56, v48, s0
	v_cvt_pk_bf16_f32 v57, v49, s0
	v_cvt_pk_bf16_f32 v58, v50, s0
	v_cvt_pk_bf16_f32 v59, v51, s0
	v_xor_b32_e32 v60, 0x4000, v8
	ds_write_b16 v60, v52
	ds_write_b16 v60, v53 offset:132
	ds_write_b16 v60, v54 offset:264
	ds_write_b16 v60, v55 offset:396
	ds_write_b16 v60, v56 offset:528
	ds_write_b16 v60, v57 offset:660
	ds_write_b16 v60, v58 offset:792
	ds_write_b16 v60, v59 offset:924
	s_waitcnt lgkmcnt(0)
	s_barrier
	ds_read2_b32 v[14:15], v9 offset1:1
	ds_read2_b32 v[16:17], v9 offset0:2 offset1:3
	v_xor_b32_e32 v61, 0x4000, v9
	ds_read2_b32 v[44:45], v61 offset1:1
	ds_read2_b32 v[46:47], v61 offset0:2 offset1:3
	s_waitcnt lgkmcnt(0)
	global_store_dwordx4 v[6:7], v[14:17], off
	s_mov_b64 s[54:55], 0x58000
	v_lshl_add_u64 v[62:63], v[6:7], 0, s[54:55]
	global_store_dwordx4 v[62:63], v[44:47], off
; __device__ __forceinline__ u16 f2bf(float a) { return (u16)(pack2(a, 0.f) & 0xffffu); }
;     ...
;   {
;     int k = t >> 3, n0 = (t & 7) * 8;
;     const float4* s = (const float4*)(src + (size_t)(kt * 64 + k) * N + ntile * 64 + n0);
;     float4 a = s[0], b = s[1];
;     tl[(n0 + 0) * 66 + k] = f2bf(a.x); tl[(n0 + 1) * 66 + k] = f2bf(a.y);
;     tl[(n0 + 2) * 66 + k] = f2bf(a.z); tl[(n0 + 3) * 66 + k] = f2bf(a.w);
;     tl[(n0 + 4) * 66 + k] = f2bf(b.x); tl[(n0 + 5) * 66 + k] = f2bf(b.y);
;     tl[(n0 + 6) * 66 + k] = f2bf(b.z); tl[(n0 + 7) * 66 + k] = f2bf(b.w);
;   }
;   __syncthreads();
;   {
;     int n = t >> 3, kk0 = (t & 7) * 8;
;     int ng = ntile * 64 + n, np = ng;
;     if (mode == 1) {
;       if (ng >= 1792) { int j = ng - 1792; int hb = 0; if (j >= 1024) { j -= 1024; hb = 32; } np = 1792 + (j >> 5) * 64 + hb + (j & 31); }
;     } else if (mode == 2) {
;       int j = ng, hb = 0; if (j >= DFF) { j -= DFF; hb = 32; } np = (j >> 5) * 64 + hb + (j & 31);
;     }
;     const uint32_t* r = (const uint32_t*)(tl + n * 66 + kk0);
;     uint4 v = make_uint4(r[0], r[1], r[2], r[3]);
;     *(uint4*)(dst + (size_t)np * dld + kt * 64 + kk0) = v;
; __global__ void __launch_bounds__(NTHREADS, 2) fwd_megakernel(Params p_arg) {
;     ...
;       else if (r < 2880) { r -= 1472; transpose_tile(pk->w_ffn_in + (size_t)l * 1024 * 2 * DFF, wl + WOFF_FI, 1024, 2 * DFF, r / 88, r % 88, 2, shm, tid); }
.LBB0_44:
	s_andn2_b64 vcc, exec, s[14:15]
	s_cbranch_vccnz .LBB0_46
	s_mov_b64 s[14:15], s[44:45]
	s_mul_i32 s34, s12, 0x1600000
	s_mul_hi_i32 s4, s12, 0x1600000
	s_waitcnt lgkmcnt(0)
	s_add_u32 s14, s14, s34
	s_addc_u32 s15, s15, s4
	s_add_i32 s4, s33, 0xfa40
	s_and_b32 s34, s4, 0xffff
	s_mul_i32 s34, s34, 0xba2f
	s_lshr_b32 s35, s34, 16
	s_lshr_b32 s34, s34, 22
	s_mulk_i32 s34, 0x58
	s_sub_i32 s4, s4, s34
	s_and_b32 s34, s35, 0xffc0
	v_add_u32_e32 v5, s34, v1
	v_mov_b64_e32 v[6:7], s[14:15]
	v_mad_i64_i32 v[6:7], s[14:15], v5, s27, v[6:7]
	s_lshl_b32 s4, s4, 6
	s_and_b32 s14, s4, 0xffc0
	s_lshl_b32 s4, s14, 2
	v_lshl_add_u64 v[6:7], v[6:7], 0, s[4:5]
	v_lshl_add_u64 v[6:7], v[6:7], 0, v[2:3]
	global_load_dwordx4 v[14:17], v[6:7], off
	global_load_dwordx4 v[18:21], v[6:7], off offset:16
	global_load_dwordx4 v[44:47], v[6:7], off offset:256
	global_load_dwordx4 v[48:51], v[6:7], off offset:272
	v_add_u32_e32 v6, s14, v1
	v_add_u32_e32 v7, 0xfffff500, v6
	v_cmp_lt_i32_e32 vcc, s28, v6
	s_lshl_b32 s4, s34, 1
	v_mov_b32_e32 v5, v3
	v_cndmask_b32_e32 v6, v6, v7, vcc
	v_lshlrev_b32_e32 v7, 1, v6
	v_cndmask_b32_e64 v13, 0, 32, vcc
	v_and_b32_e32 v6, 31, v6
	v_and_b32_e32 v7, 0xffffffc0, v7
	v_or3_b32 v6, v6, v13, v7
	v_ashrrev_i32_e32 v7, 31, v6
	v_lshlrev_b64 v[6:7], 11, v[6:7]
	v_lshl_add_u64 v[6:7], s[10:11], 0, v[6:7]
	v_lshl_add_u64 v[6:7], v[6:7], 0, s[4:5]
	v_lshl_add_u64 v[6:7], v[6:7], 0, v[4:5]
	v_add_co_u32_e32 v6, vcc, 0xb80000, v6
	s_waitcnt vmcnt(3)
	v_cvt_pk_bf16_f32 v5, v14, s0
	v_cvt_pk_bf16_f32 v13, v15, s0
	v_cvt_pk_bf16_f32 v14, v16, s0
	v_cvt_pk_bf16_f32 v15, v17, s0
	s_waitcnt vmcnt(2)
	v_cvt_pk_bf16_f32 v16, v18, s0
	v_cvt_pk_bf16_f32 v17, v19, s0
	v_cvt_pk_bf16_f32 v18, v20, s0
	v_cvt_pk_bf16_f32 v19, v21, s0
	ds_write_b16 v8, v5
	ds_write_b16 v8, v13 offset:132
	ds_write_b16 v8, v14 offset:264
	ds_write_b16 v8, v15 offset:396
	ds_write_b16 v8, v16 offset:528
	ds_write_b16 v8, v17 offset:660
	ds_write_b16 v8, v18 offset:792
	ds_write_b16 v8, v19 offset:924
	s_waitcnt vmcnt(1)
	v_cvt_pk_bf16_f32 v52, v44, s0
	v_cvt_pk_bf16_f32 v53, v45, s0
	v_cvt_pk_bf16_f32 v54, v46, s0
	v_cvt_pk_bf16_f32 v55, v47, s0
	s_waitcnt vmcnt(0)
	v_cvt_pk_bf16_f32 v56, v48, s0
	v_cvt_pk_bf16_f32 v57, v49, s0
	v_cvt_pk_bf16_f32 v58, v50, s0
	v_cvt_pk_bf16_f32 v59, v51, s0
	v_xor_b32_e32 v60, 0x4000, v8
	ds_write_b16 v60, v52
	ds_write_b16 v60, v53 offset:132
	ds_write_b16 v60, v54 offset:264
	ds_write_b16 v60, v55 offset:396
	ds_write_b16 v60, v56 offset:528
	ds_write_b16 v60, v57 offset:660
	ds_write_b16 v60, v58 offset:792
	ds_write_b16 v60, v59 offset:924
	s_waitcnt lgkmcnt(0)
	s_barrier
	ds_read2_b32 v[14:15], v9 offset1:1
	ds_read2_b32 v[16:17], v9 offset0:2 offset1:3
	v_xor_b32_e32 v61, 0x4000, v9
	ds_read2_b32 v[44:45], v61 offset1:1
	ds_read2_b32 v[46:47], v61 offset0:2 offset1:3
	v_addc_co_u32_e32 v7, vcc, 0, v7, vcc
	s_waitcnt lgkmcnt(0)
	global_store_dwordx4 v[6:7], v[14:17], off
	s_mov_b64 s[54:55], 0x40000
	v_lshl_add_u64 v[62:63], v[6:7], 0, s[54:55]
	global_store_dwordx4 v[62:63], v[44:47], off

; __device__ __forceinline__ u16 f2bf(float a) { return (u16)(pack2(a, 0.f) & 0xffffu); }
;     ...
;   {
;     int k = t >> 3, n0 = (t & 7) * 8;
;     const float4* s = (const float4*)(src + (size_t)(kt * 64 + k) * N + ntile * 64 + n0);
;     float4 a = s[0], b = s[1];
;     tl[(n0 + 0) * 66 + k] = f2bf(a.x); tl[(n0 + 1) * 66 + k] = f2bf(a.y);
;     tl[(n0 + 2) * 66 + k] = f2bf(a.z); tl[(n0 + 3) * 66 + k] = f2bf(a.w);
;     tl[(n0 + 4) * 66 + k] = f2bf(b.x); tl[(n0 + 5) * 66 + k] = f2bf(b.y);
;     tl[(n0 + 6) * 66 + k] = f2bf(b.z); tl[(n0 + 7) * 66 + k] = f2bf(b.w);
;   }
;   __syncthreads();
;   {
;     int n = t >> 3, kk0 = (t & 7) * 8;
;     int ng = ntile * 64 + n, np = ng;
;     if (mode == 1) {
;       if (ng >= 1792) { int j = ng - 1792; int hb = 0; if (j >= 1024) { j -= 1024; hb = 32; } np = 1792 + (j >> 5) * 64 + hb + (j & 31); }
;     } else if (mode == 2) {
;       int j = ng, hb = 0; if (j >= DFF) { j -= DFF; hb = 32; } np = (j >> 5) * 64 + hb + (j & 31);
;     }
;     const uint32_t* r = (const uint32_t*)(tl + n * 66 + kk0);
;     uint4 v = make_uint4(r[0], r[1], r[2], r[3]);
;     *(uint4*)(dst + (size_t)np * dld + kt * 64 + kk0) = v;
; __global__ void __launch_bounds__(NTHREADS, 2) fwd_megakernel(Params p_arg) {
;     ...
;       else if (r < 1472) { r -= 1216; transpose_tile(pk->w_o + (size_t)l * 1024 * 1024, wl + WOFF_O, 1024, 1024, r / 16, r % 16, 0, shm, tid); }
.LBB0_47:
	s_andn2_b64 vcc, exec, s[14:15]
	s_cbranch_vccnz .LBB0_49
	s_mov_b64 s[14:15], s[46:47]
	s_lshl_b64 s[34:35], s[12:13], 22
	s_mul_i32 s4, s12, 0xffffc800
	v_mov_b32_e32 v5, v3
	s_waitcnt lgkmcnt(0)
	s_add_u32 s14, s14, s34
	s_addc_u32 s15, s15, s35
	s_add_i32 s4, s18, s4
	s_and_b32 s4, s4, 0x1fc0
	s_add_i32 s34, s4, 0xffffed00
	v_add_u32_e32 v6, s34, v1
	v_ashrrev_i32_e32 v7, 31, v6
	s_and_b32 s36, s20, 0x3c0
	v_lshlrev_b64 v[6:7], 12, v[6:7]
	v_lshl_add_u64 v[6:7], s[14:15], 0, v[6:7]
	s_lshl_b32 s4, s36, 2
	v_lshl_add_u64 v[6:7], v[6:7], 0, s[4:5]
	v_lshl_add_u64 v[6:7], v[6:7], 0, v[2:3]
	global_load_dwordx4 v[14:17], v[6:7], off
	global_load_dwordx4 v[18:21], v[6:7], off offset:16
	global_load_dwordx4 v[44:47], v[6:7], off offset:256
	global_load_dwordx4 v[48:51], v[6:7], off offset:272
	v_add_u32_e32 v6, s36, v1
	v_ashrrev_i32_e32 v7, 31, v6
	v_lshlrev_b64 v[6:7], 11, v[6:7]
	s_mov_b32 s35, s5
	v_lshl_add_u64 v[6:7], s[10:11], 0, v[6:7]
	v_lshl_add_u64 v[6:7], s[34:35], 1, v[6:7]
	v_lshl_add_u64 v[6:7], v[6:7], 0, v[4:5]
	v_add_co_u32_e32 v6, vcc, 0x980000, v6
	s_waitcnt vmcnt(3)
	v_cvt_pk_bf16_f32 v5, v14, s0
	v_cvt_pk_bf16_f32 v13, v15, s0
	v_cvt_pk_bf16_f32 v14, v16, s0
	v_cvt_pk_bf16_f32 v15, v17, s0
	s_waitcnt vmcnt(2)
	v_cvt_pk_bf16_f32 v16, v18, s0
	v_cvt_pk_bf16_f32 v17, v19, s0
	v_cvt_pk_bf16_f32 v18, v20, s0
	v_cvt_pk_bf16_f32 v19, v21, s0
	ds_write_b16 v8, v5
	ds_write_b16 v8, v13 offset:132
	ds_write_b16 v8, v14 offset:264
	ds_write_b16 v8, v15 offset:396
	ds_write_b16 v8, v16 offset:528
	ds_write_b16 v8, v17 offset:660
	ds_write_b16 v8, v18 offset:792
	ds_write_b16 v8, v19 offset:924
	s_waitcnt vmcnt(1)
	v_cvt_pk_bf16_f32 v52, v44, s0
	v_cvt_pk_bf16_f32 v53, v45, s0
	v_cvt_pk_bf16_f32 v54, v46, s0
	v_cvt_pk_bf16_f32 v55, v47, s0
	s_waitcnt vmcnt(0)
	v_cvt_pk_bf16_f32 v56, v48, s0
	v_cvt_pk_bf16_f32 v57, v49, s0
	v_cvt_pk_bf16_f32 v58, v50, s0
	v_cvt_pk_bf16_f32 v59, v51, s0
	v_xor_b32_e32 v60, 0x4000, v8
	ds_write_b16 v60, v52
	ds_write_b16 v60, v53 offset:132
	ds_write_b16 v60, v54 offset:264
	ds_write_b16 v60, v55 offset:396
	ds_write_b16 v60, v56 offset:528
	ds_write_b16 v60, v57 offset:660
	ds_write_b16 v60, v58 offset:792
	ds_write_b16 v60, v59 offset:924
	s_waitcnt lgkmcnt(0)
	s_barrier
	ds_read2_b32 v[14:15], v9 offset1:1
	ds_read2_b32 v[16:17], v9 offset0:2 offset1:3
	v_xor_b32_e32 v61, 0x4000, v9
	ds_read2_b32 v[44:45], v61 offset1:1
	ds_read2_b32 v[46:47], v61 offset0:2 offset1:3
	v_addc_co_u32_e32 v7, vcc, 0, v7, vcc
	s_waitcnt lgkmcnt(0)
	global_store_dwordx4 v[6:7], v[14:17], off
	s_mov_b64 s[54:55], 0x20000
	v_lshl_add_u64 v[62:63], v[6:7], 0, s[54:55]
	global_store_dwordx4 v[62:63], v[44:47], off

; __device__ __forceinline__ u16 f2bf(float a) { return (u16)(pack2(a, 0.f) & 0xffffu); }
;     ...
;   {
;     int k = t >> 3, n0 = (t & 7) * 8;
;     const float4* s = (const float4*)(src + (size_t)(kt * 64 + k) * N + ntile * 64 + n0);
;     float4 a = s[0], b = s[1];
;     tl[(n0 + 0) * 66 + k] = f2bf(a.x); tl[(n0 + 1) * 66 + k] = f2bf(a.y);
;     tl[(n0 + 2) * 66 + k] = f2bf(a.z); tl[(n0 + 3) * 66 + k] = f2bf(a.w);
;     tl[(n0 + 4) * 66 + k] = f2bf(b.x); tl[(n0 + 5) * 66 + k] = f2bf(b.y);
;     tl[(n0 + 6) * 66 + k] = f2bf(b.z); tl[(n0 + 7) * 66 + k] = f2bf(b.w);
;   }
;   __syncthreads();
;   {
;     int n = t >> 3, kk0 = (t & 7) * 8;
;     int ng = ntile * 64 + n, np = ng;
;     if (mode == 1) {
;       if (ng >= 1792) { int j = ng - 1792; int hb = 0; if (j >= 1024) { j -= 1024; hb = 32; } np = 1792 + (j >> 5) * 64 + hb + (j & 31); }
;     } else if (mode == 2) {
;       int j = ng, hb = 0; if (j >= DFF) { j -= DFF; hb = 32; } np = (j >> 5) * 64 + hb + (j & 31);
;     }
;     const uint32_t* r = (const uint32_t*)(tl + n * 66 + kk0);
;     uint4 v = make_uint4(r[0], r[1], r[2], r[3]);
;     *(uint4*)(dst + (size_t)np * dld + kt * 64 + kk0) = v;
; __global__ void __launch_bounds__(NTHREADS, 2) fwd_megakernel(Params p_arg) {
;     ...
;       else if (r < 1216) { r -= 1088; transpose_tile(pk->w_b + (size_t)l * 512 * 1024, wl + WOFF_A + 512, 512, 1024, r / 16, r % 16, 0, shm, tid, 1024); }
.LBB0_50:
	s_andn2_b64 vcc, exec, s[14:15]
	s_cbranch_vccnz .LBB0_52
	s_mov_b64 s[14:15], s[48:49]
	s_lshl_b64 s[34:35], s[12:13], 21
	s_mul_i32 s4, s12, 0xffffc800
	v_mov_b32_e32 v5, v3
	s_waitcnt lgkmcnt(0)
	s_add_u32 s14, s14, s34
	s_addc_u32 s15, s15, s35
	s_add_i32 s4, s18, s4
	s_and_b32 s4, s4, 0x1fc0
	s_add_i32 s34, s4, 0xffffef00
	v_add_u32_e32 v6, s34, v1
	v_ashrrev_i32_e32 v7, 31, v6
	s_and_b32 s36, s20, 0x3c0
	v_lshlrev_b64 v[6:7], 12, v[6:7]
	v_lshl_add_u64 v[6:7], s[14:15], 0, v[6:7]
	s_lshl_b32 s4, s36, 2
	v_lshl_add_u64 v[6:7], v[6:7], 0, s[4:5]
	v_lshl_add_u64 v[6:7], v[6:7], 0, v[2:3]
	global_load_dwordx4 v[14:17], v[6:7], off
	global_load_dwordx4 v[18:21], v[6:7], off offset:16
	global_load_dwordx4 v[44:47], v[6:7], off offset:256
	global_load_dwordx4 v[48:51], v[6:7], off offset:272
	v_add_u32_e32 v6, s36, v1
	v_ashrrev_i32_e32 v7, 31, v6
	v_lshlrev_b64 v[6:7], 11, v[6:7]
	s_mov_b32 s35, s5
	v_lshl_add_u64 v[6:7], s[10:11], 0, v[6:7]
	v_lshl_add_u64 v[6:7], s[34:35], 1, v[6:7]
	v_lshl_add_u64 v[6:7], v[6:7], 0, v[4:5]
	v_add_co_u32_e32 v6, vcc, 0x780000, v6
	s_waitcnt vmcnt(3)
	v_cvt_pk_bf16_f32 v5, v14, s0
	v_cvt_pk_bf16_f32 v13, v15, s0
	v_cvt_pk_bf16_f32 v14, v16, s0
	v_cvt_pk_bf16_f32 v15, v17, s0
	s_waitcnt vmcnt(2)
	v_cvt_pk_bf16_f32 v16, v18, s0
	v_cvt_pk_bf16_f32 v17, v19, s0
	v_cvt_pk_bf16_f32 v18, v20, s0
	v_cvt_pk_bf16_f32 v19, v21, s0
	ds_write_b16 v8, v5
	ds_write_b16 v8, v13 offset:132
	ds_write_b16 v8, v14 offset:264
	ds_write_b16 v8, v15 offset:396
	ds_write_b16 v8, v16 offset:528
	ds_write_b16 v8, v17 offset:660
	ds_write_b16 v8, v18 offset:792
	ds_write_b16 v8, v19 offset:924
	s_waitcnt vmcnt(1)
	v_cvt_pk_bf16_f32 v52, v44, s0
	v_cvt_pk_bf16_f32 v53, v45, s0
	v_cvt_pk_bf16_f32 v54, v46, s0
	v_cvt_pk_bf16_f32 v55, v47, s0
	s_waitcnt vmcnt(0)
	v_cvt_pk_bf16_f32 v56, v48, s0
	v_cvt_pk_bf16_f32 v57, v49, s0
	v_cvt_pk_bf16_f32 v58, v50, s0
	v_cvt_pk_bf16_f32 v59, v51, s0
	v_xor_b32_e32 v60, 0x4000, v8
	ds_write_b16 v60, v52
	ds_write_b16 v60, v53 offset:132
	ds_write_b16 v60, v54 offset:264
	ds_write_b16 v60, v55 offset:396
	ds_write_b16 v60, v56 offset:528
	ds_write_b16 v60, v57 offset:660
	ds_write_b16 v60, v58 offset:792
	ds_write_b16 v60, v59 offset:924
	s_waitcnt lgkmcnt(0)
	s_barrier
	ds_read2_b32 v[14:15], v9 offset1:1
	ds_read2_b32 v[16:17], v9 offset0:2 offset1:3
	v_xor_b32_e32 v61, 0x4000, v9
	ds_read2_b32 v[44:45], v61 offset1:1
	ds_read2_b32 v[46:47], v61 offset0:2 offset1:3
	v_addc_co_u32_e32 v7, vcc, 0, v7, vcc
	s_waitcnt lgkmcnt(0)
	global_store_dwordx4 v[6:7], v[14:17], off offset:1024
	s_mov_b64 s[54:55], 0x20000
	v_lshl_add_u64 v[62:63], v[6:7], 0, s[54:55]
	global_store_dwordx4 v[62:63], v[44:47], off offset:1024

; __device__ __forceinline__ u16 f2bf(float a) { return (u16)(pack2(a, 0.f) & 0xffffu); }
;     ...
;   {
;     int k = t >> 3, n0 = (t & 7) * 8;
;     const float4* s = (const float4*)(src + (size_t)(kt * 64 + k) * N + ntile * 64 + n0);
;     float4 a = s[0], b = s[1];
;     tl[(n0 + 0) * 66 + k] = f2bf(a.x); tl[(n0 + 1) * 66 + k] = f2bf(a.y);
;     tl[(n0 + 2) * 66 + k] = f2bf(a.z); tl[(n0 + 3) * 66 + k] = f2bf(a.w);
;     tl[(n0 + 4) * 66 + k] = f2bf(b.x); tl[(n0 + 5) * 66 + k] = f2bf(b.y);
;     tl[(n0 + 6) * 66 + k] = f2bf(b.z); tl[(n0 + 7) * 66 + k] = f2bf(b.w);
;   }
;   __syncthreads();
;   {
;     int n = t >> 3, kk0 = (t & 7) * 8;
;     int ng = ntile * 64 + n, np = ng;
;     if (mode == 1) {
;       if (ng >= 1792) { int j = ng - 1792; int hb = 0; if (j >= 1024) { j -= 1024; hb = 32; } np = 1792 + (j >> 5) * 64 + hb + (j & 31); }
;     } else if (mode == 2) {
;       int j = ng, hb = 0; if (j >= DFF) { j -= DFF; hb = 32; } np = (j >> 5) * 64 + hb + (j & 31);
;     }
;     const uint32_t* r = (const uint32_t*)(tl + n * 66 + kk0);
;     uint4 v = make_uint4(r[0], r[1], r[2], r[3]);
;     *(uint4*)(dst + (size_t)np * dld + kt * 64 + kk0) = v;
; __global__ void __launch_bounds__(NTHREADS, 2) fwd_megakernel(Params p_arg) {
;     ...
;       else if (r < 1088) { r -= 960; transpose_tile(pk->w_a + (size_t)l * 512 * 1024, wl + WOFF_A, 512, 1024, r / 16, r % 16, 0, shm, tid, 1024); }
.LBB0_53:
	s_andn2_b64 vcc, exec, s[14:15]
	s_cbranch_vccnz .LBB0_55
	s_mov_b64 s[14:15], s[50:51]
	s_lshl_b64 s[34:35], s[12:13], 21
	s_mul_i32 s4, s12, 0xffffc800
	v_mov_b32_e32 v5, v3
	s_waitcnt lgkmcnt(0)
	s_add_u32 s14, s14, s34
	s_addc_u32 s15, s15, s35
	s_add_i32 s4, s18, s4
	s_and_b32 s4, s4, 0x1fc0
	s_add_i32 s34, s4, 0xfffff100
	v_add_u32_e32 v6, s34, v1
	v_ashrrev_i32_e32 v7, 31, v6
	s_and_b32 s13, s20, 0x3c0
	v_lshlrev_b64 v[6:7], 12, v[6:7]
	v_lshl_add_u64 v[6:7], s[14:15], 0, v[6:7]
	s_lshl_b32 s4, s13, 2
	v_lshl_add_u64 v[6:7], v[6:7], 0, s[4:5]
	v_lshl_add_u64 v[6:7], v[6:7], 0, v[2:3]
	global_load_dwordx4 v[14:17], v[6:7], off
	global_load_dwordx4 v[18:21], v[6:7], off offset:16
	global_load_dwordx4 v[44:47], v[6:7], off offset:256
	global_load_dwordx4 v[48:51], v[6:7], off offset:272
	v_add_u32_e32 v6, s13, v1
	v_ashrrev_i32_e32 v7, 31, v6
	v_lshlrev_b64 v[6:7], 11, v[6:7]
	s_mov_b32 s35, s5
	v_lshl_add_u64 v[6:7], s[10:11], 0, v[6:7]
	v_lshl_add_u64 v[6:7], s[34:35], 1, v[6:7]
	v_lshl_add_u64 v[6:7], v[6:7], 0, v[4:5]
	v_add_co_u32_e32 v6, vcc, 0x780000, v6
	s_waitcnt vmcnt(3)
	v_cvt_pk_bf16_f32 v5, v14, s0
	v_cvt_pk_bf16_f32 v13, v15, s0
	v_cvt_pk_bf16_f32 v14, v16, s0
	v_cvt_pk_bf16_f32 v15, v17, s0
	s_waitcnt vmcnt(2)
	v_cvt_pk_bf16_f32 v16, v18, s0
	v_cvt_pk_bf16_f32 v17, v19, s0
	v_cvt_pk_bf16_f32 v18, v20, s0
	v_cvt_pk_bf16_f32 v19, v21, s0
	ds_write_b16 v8, v5
	ds_write_b16 v8, v13 offset:132
	ds_write_b16 v8, v14 offset:264
	ds_write_b16 v8, v15 offset:396
	ds_write_b16 v8, v16 offset:528
	ds_write_b16 v8, v17 offset:660
	ds_write_b16 v8, v18 offset:792
	ds_write_b16 v8, v19 offset:924
	s_waitcnt vmcnt(1)
	v_cvt_pk_bf16_f32 v52, v44, s0
	v_cvt_pk_bf16_f32 v53, v45, s0
	v_cvt_pk_bf16_f32 v54, v46, s0
	v_cvt_pk_bf16_f32 v55, v47, s0
	s_waitcnt vmcnt(0)
	v_cvt_pk_bf16_f32 v56, v48, s0
	v_cvt_pk_bf16_f32 v57, v49, s0
	v_cvt_pk_bf16_f32 v58, v50, s0
	v_cvt_pk_bf16_f32 v59, v51, s0
	v_xor_b32_e32 v60, 0x4000, v8
	ds_write_b16 v60, v52
	ds_write_b16 v60, v53 offset:132
	ds_write_b16 v60, v54 offset:264
	ds_write_b16 v60, v55 offset:396
	ds_write_b16 v60, v56 offset:528
	ds_write_b16 v60, v57 offset:660
	ds_write_b16 v60, v58 offset:792
	ds_write_b16 v60, v59 offset:924
	s_waitcnt lgkmcnt(0)
	s_barrier
	ds_read2_b32 v[14:15], v9 offset1:1
	ds_read2_b32 v[16:17], v9 offset0:2 offset1:3
	v_xor_b32_e32 v61, 0x4000, v9
	ds_read2_b32 v[44:45], v61 offset1:1
	ds_read2_b32 v[46:47], v61 offset0:2 offset1:3
	v_addc_co_u32_e32 v7, vcc, 0, v7, vcc
	s_waitcnt lgkmcnt(0)
	global_store_dwordx4 v[6:7], v[14:17], off
	s_mov_b64 s[54:55], 0x20000
	v_lshl_add_u64 v[62:63], v[6:7], 0, s[54:55]
	global_store_dwordx4 v[62:63], v[44:47], off

; __device__ __forceinline__ u16 f2bf(float a) { return (u16)(pack2(a, 0.f) & 0xffffu); }
;     ...
;   {
;     int k = t >> 3, n0 = (t & 7) * 8;
;     const float4* s = (const float4*)(src + (size_t)(kt * 64 + k) * N + ntile * 64 + n0);
;     float4 a = s[0], b = s[1];
;     tl[(n0 + 0) * 66 + k] = f2bf(a.x); tl[(n0 + 1) * 66 + k] = f2bf(a.y);
;     tl[(n0 + 2) * 66 + k] = f2bf(a.z); tl[(n0 + 3) * 66 + k] = f2bf(a.w);
;     tl[(n0 + 4) * 66 + k] = f2bf(b.x); tl[(n0 + 5) * 66 + k] = f2bf(b.y);
;     tl[(n0 + 6) * 66 + k] = f2bf(b.z); tl[(n0 + 7) * 66 + k] = f2bf(b.w);
;   }
;   __syncthreads();
;   {
;     int n = t >> 3, kk0 = (t & 7) * 8;
;     int ng = ntile * 64 + n, np = ng;
;     if (mode == 1) {
;       if (ng >= 1792) { int j = ng - 1792; int hb = 0; if (j >= 1024) { j -= 1024; hb = 32; } np = 1792 + (j >> 5) * 64 + hb + (j & 31); }
; __global__ void __launch_bounds__(NTHREADS, 2) fwd_megakernel(Params p_arg) {
;     ...
;     for (int t = blockIdx.x; t < NLAYER * 3584; t += gridDim.x) {
;       int l = t / 3584, r = t - l * 3584;
;       u16* wl = WB + (size_t)l * WLAYER_E;
;       if (r < 960) { transpose_tile(pk->w_in + (size_t)l * 1024 * INW, wl + WOFF_IN, 1024, INW, r / 60, r % 60, 1, shm, tid); }
.LBB0_56:
	s_andn2_b64 vcc, exec, s[14:15]
	s_cbranch_vccnz .LBB0_37
	s_mov_b32 s56, s12
	s_mov_b32 s57, 0
.Lwin_again:
	s_mov_b64 s[14:15], s[52:53]
	s_mul_hi_i32 s4, s12, 0xf00000
	s_mul_i32 s12, s12, 0xf00000
	s_mul_hi_i32 s13, s33, 0x88888889
	s_waitcnt lgkmcnt(0)
	s_add_u32 s14, s14, s12
	s_addc_u32 s15, s15, s4
	s_add_i32 s13, s13, s33
	s_lshr_b32 s4, s13, 31
	s_ashr_i32 s12, s13, 5
	s_add_i32 s4, s12, s4
	s_mul_i32 s12, s4, 60
	s_sub_i32 s13, s33, s12
	s_lshl_b32 s12, s4, 6
	v_add_u32_e32 v5, s12, v1
	v_mov_b64_e32 v[6:7], s[14:15]
	v_mad_i64_i32 v[6:7], s[14:15], v5, s29, v[6:7]
	s_lshl_b32 s14, s13, 6
	s_ashr_i32 s15, s14, 31
	v_lshl_add_u64 v[6:7], s[14:15], 2, v[6:7]
	v_lshl_add_u64 v[6:7], v[6:7], 0, v[2:3]
	global_load_dwordx4 v[14:17], v[6:7], off
	global_load_dwordx4 v[18:21], v[6:7], off offset:16
	v_add_u32_e32 v6, s14, v1
	v_cmp_lt_i32_e32 vcc, s30, v6
	s_waitcnt vmcnt(1)
	v_cvt_pk_bf16_f32 v5, v14, s0
	v_cvt_pk_bf16_f32 v7, v15, s0
	v_cvt_pk_bf16_f32 v13, v16, s0
	v_cvt_pk_bf16_f32 v14, v17, s0
	s_waitcnt vmcnt(0)
	v_cvt_pk_bf16_f32 v15, v18, s0
	v_cvt_pk_bf16_f32 v16, v19, s0
	v_cvt_pk_bf16_f32 v17, v20, s0
	v_cvt_pk_bf16_f32 v18, v21, s0
	ds_write_b16 v8, v5
	ds_write_b16 v8, v7 offset:132
	ds_write_b16 v8, v13 offset:264
	ds_write_b16 v8, v14 offset:396
	ds_write_b16 v8, v15 offset:528
	ds_write_b16 v8, v16 offset:660
	ds_write_b16 v8, v17 offset:792
	ds_write_b16 v8, v18 offset:924
	s_waitcnt lgkmcnt(0)
	s_barrier
	s_and_saveexec_b64 s[14:15], vcc
	s_cbranch_execz .LBB0_36
	v_cmp_lt_u32_e32 vcc, s28, v6
	s_nop 1
	v_cndmask_b32_e32 v7, v11, v12, vcc
	v_add_lshl_u32 v6, v7, v6, 1
	v_cndmask_b32_e64 v5, 0, 32, vcc
	v_and_b32_e32 v6, 0x7fffffc0, v6
	v_or3_b32 v5, v6, v5, v10
	v_add_u32_e32 v6, 0x700, v5
	s_branch .LBB0_36
